# L2 GEMM cross-tile prefetch: last k-step issues the next tile's first-stage LDS-DMA ahead of the epilogue stores (counted vmcnt 63)
# speedup vs baseline: 1.0027x; 1.0027x over previous
.LBB0_259:
	s_add_i32 s2, s6, s22
	s_mul_hi_i32 s3, s2, 0x8d3dcb09
	s_add_i32 s3, s3, s2
	s_lshr_b32 s4, s3, 31
	s_ashr_i32 s3, s3, 4
	s_add_i32 s3, s3, s4
	s_mul_i32 s4, s3, 29
	s_lshl_b32 s3, s3, 7
	s_sub_i32 s2, s2, s4
	s_lshl_b32 s2, s2, 7
	s_lshl_b32 s62, s3, 11
	s_add_u32 s54, s82, s62
	s_addc_u32 s55, s83, 0
	s_add_u32 s54, s54, 0x3000000
	s_addc_u32 s55, s55, 0
	s_lshl_b32 s62, s2, 11
	s_add_u32 s56, s60, s62
	s_addc_u32 s57, s61, 0
	s_add_u32 m0, s58, 0x0
	s_nop 0
	global_load_lds_dwordx4 v152, s[54:55]
	s_add_u32 m0, m0, 0x400
	s_nop 0
	global_load_lds_dwordx4 v153, s[54:55]
	s_add_u32 m0, m0, 0x400
	s_nop 0
	global_load_lds_dwordx4 v154, s[54:55]
	s_add_u32 m0, m0, 0x400
	s_nop 0
	global_load_lds_dwordx4 v155, s[54:55]
	s_add_u32 m0, m0, 0x3400
	s_nop 0
	global_load_lds_dwordx4 v152, s[56:57]
	s_add_u32 m0, m0, 0x400
	s_nop 0
	global_load_lds_dwordx4 v153, s[56:57]
	s_add_u32 m0, m0, 0x400
	s_nop 0
	global_load_lds_dwordx4 v154, s[56:57]
	s_add_u32 m0, m0, 0x400
	s_nop 0
	global_load_lds_dwordx4 v155, s[56:57]
	s_waitcnt vmcnt(0)
	s_branch .Lg2_go
.Lg2_next:
	s_add_i32 s2, s6, s22
	s_mul_hi_i32 s3, s2, 0x8d3dcb09
	s_add_i32 s3, s3, s2
	s_lshr_b32 s4, s3, 31
	s_ashr_i32 s3, s3, 4
	s_add_i32 s3, s3, s4
	s_mul_i32 s4, s3, 29
	s_lshl_b32 s3, s3, 7
	s_sub_i32 s2, s2, s4
	s_lshl_b32 s2, s2, 7
	s_waitcnt vmcnt(63)
.Lg2_go:
	v_mov_b32_e32 v60, 0
	v_mov_b32_e32 v61, v60
	v_mov_b32_e32 v62, v60
	v_mov_b32_e32 v63, v60
	v_mov_b32_e32 v40, v60
	v_mov_b32_e32 v41, v60
	v_mov_b32_e32 v42, v60
	v_mov_b32_e32 v43, v60
	v_mov_b32_e32 v44, v60
	v_mov_b32_e32 v45, v60
	v_mov_b32_e32 v46, v60
	v_mov_b32_e32 v47, v60
	v_mov_b32_e32 v48, v60
	v_mov_b32_e32 v49, v60
	v_mov_b32_e32 v50, v60
	v_mov_b32_e32 v51, v60
	v_mov_b32_e32 v52, v60
	v_mov_b32_e32 v53, v60
	v_mov_b32_e32 v54, v60
	v_mov_b32_e32 v55, v60
	v_mov_b32_e32 v56, v60
	v_mov_b32_e32 v57, v60
	v_mov_b32_e32 v58, v60
	v_mov_b32_e32 v59, v60
	v_mov_b32_e32 v16, v60
	v_mov_b32_e32 v17, v60
	v_mov_b32_e32 v18, v60
	v_mov_b32_e32 v19, v60
	v_mov_b32_e32 v12, v60
	v_mov_b32_e32 v13, v60
	v_mov_b32_e32 v14, v60
	v_mov_b32_e32 v15, v60
	v_mov_b32_e32 v20, v60
	v_mov_b32_e32 v21, v60
	v_mov_b32_e32 v22, v60
	v_mov_b32_e32 v23, v60
	v_mov_b32_e32 v0, v60
	v_mov_b32_e32 v1, v60
	v_mov_b32_e32 v2, v60
	v_mov_b32_e32 v3, v60
	v_mov_b32_e32 v4, v60
	v_mov_b32_e32 v5, v60
	v_mov_b32_e32 v6, v60
	v_mov_b32_e32 v7, v60
	v_mov_b32_e32 v8, v60
	v_mov_b32_e32 v9, v60
	v_mov_b32_e32 v10, v60
	v_mov_b32_e32 v11, v60
	v_mov_b32_e32 v24, v60
	v_mov_b32_e32 v25, v60
	v_mov_b32_e32 v26, v60
	v_mov_b32_e32 v27, v60
	v_mov_b32_e32 v28, v60
	v_mov_b32_e32 v29, v60
	v_mov_b32_e32 v30, v60
	v_mov_b32_e32 v31, v60
	v_mov_b32_e32 v32, v60
	v_mov_b32_e32 v33, v60
	v_mov_b32_e32 v34, v60
	v_mov_b32_e32 v35, v60
	v_mov_b32_e32 v36, v60
	v_mov_b32_e32 v37, v60
	v_mov_b32_e32 v38, v60
	v_mov_b32_e32 v39, v60
	s_mov_b32 s59, 7
	s_barrier
.Lg2_loop:
	s_add_u32 s54, s54, 0x80
	s_addc_u32 s55, s55, 0
	s_add_u32 s56, s56, 0x80
	s_addc_u32 s57, s57, 0
	ds_read_b128 v[64:67], v156
	ds_read_b128 v[68:71], v158 offset:16384
	ds_read_b128 v[80:83], v159 offset:16384
	ds_read_b128 v[72:75], v157
	ds_read_b128 v[76:79], v158 offset:18432
	ds_read_b128 v[92:95], v159 offset:18432
	ds_read_b128 v[84:87], v158 offset:20480
	ds_read_b128 v[116:119], v159 offset:20480
	ds_read_b128 v[88:91], v158 offset:22528
	ds_read_b128 v[120:123], v159 offset:22528
	s_waitcnt lgkmcnt(8)
	v_mfma_f32_16x16x32_bf16 v[36:39], v[64:67], v[68:71], v[36:39]
	s_waitcnt lgkmcnt(5)
	v_mfma_f32_16x16x32_bf16 v[32:35], v[64:67], v[76:79], v[32:35]
	s_waitcnt lgkmcnt(3)
	s_add_u32 m0, s58, 0x8000
	v_mfma_f32_16x16x32_bf16 v[28:31], v[64:67], v[84:87], v[28:31]
	global_load_lds_dwordx4 v152, s[54:55]
	s_waitcnt lgkmcnt(1)
	v_mfma_f32_16x16x32_bf16 v[24:27], v[64:67], v[88:91], v[24:27]
	ds_read_b128 v[64:67], v156 offset:2048
	ds_read_b128 v[124:127], v157 offset:2048
	s_waitcnt lgkmcnt(1)
	v_mfma_f32_16x16x32_bf16 v[8:11], v[64:67], v[68:71], v[8:11]
	s_add_u32 m0, m0, 0x400
	v_mfma_f32_16x16x32_bf16 v[4:7], v[64:67], v[76:79], v[4:7]
	global_load_lds_dwordx4 v153, s[54:55]
	v_mfma_f32_16x16x32_bf16 v[0:3], v[64:67], v[84:87], v[0:3]
	v_mfma_f32_16x16x32_bf16 v[20:23], v[64:67], v[88:91], v[20:23]
	ds_read_b128 v[64:67], v156 offset:4096
	ds_read_b128 v[128:131], v157 offset:4096
	s_waitcnt lgkmcnt(1)
	s_add_u32 m0, m0, 0x400
	v_mfma_f32_16x16x32_bf16 v[12:15], v[64:67], v[68:71], v[12:15]
	global_load_lds_dwordx4 v154, s[54:55]
	v_mfma_f32_16x16x32_bf16 v[16:19], v[64:67], v[76:79], v[16:19]
	v_mfma_f32_16x16x32_bf16 v[56:59], v[64:67], v[84:87], v[56:59]
	s_add_u32 m0, m0, 0x400
	v_mfma_f32_16x16x32_bf16 v[52:55], v[64:67], v[88:91], v[52:55]
	global_load_lds_dwordx4 v155, s[54:55]
	ds_read_b128 v[64:67], v156 offset:6144
	ds_read_b128 v[132:135], v157 offset:6144
	s_waitcnt lgkmcnt(1)
	v_mfma_f32_16x16x32_bf16 v[48:51], v[64:67], v[68:71], v[48:51]
	v_mfma_f32_16x16x32_bf16 v[44:47], v[64:67], v[76:79], v[44:47]
	s_add_u32 m0, m0, 0x3400
	v_mfma_f32_16x16x32_bf16 v[40:43], v[64:67], v[84:87], v[40:43]
	global_load_lds_dwordx4 v152, s[56:57]
	v_mfma_f32_16x16x32_bf16 v[60:63], v[64:67], v[88:91], v[60:63]
	v_mfma_f32_16x16x32_bf16 v[36:39], v[72:75], v[80:83], v[36:39]
	s_add_u32 m0, m0, 0x400
	v_mfma_f32_16x16x32_bf16 v[32:35], v[72:75], v[92:95], v[32:35]
	global_load_lds_dwordx4 v153, s[56:57]
	v_mfma_f32_16x16x32_bf16 v[28:31], v[72:75], v[116:119], v[28:31]
	v_mfma_f32_16x16x32_bf16 v[24:27], v[72:75], v[120:123], v[24:27]
	s_add_u32 m0, m0, 0x400
	v_mfma_f32_16x16x32_bf16 v[8:11], v[124:127], v[80:83], v[8:11]
	global_load_lds_dwordx4 v154, s[56:57]
	v_mfma_f32_16x16x32_bf16 v[4:7], v[124:127], v[92:95], v[4:7]
	v_mfma_f32_16x16x32_bf16 v[0:3], v[124:127], v[116:119], v[0:3]
	s_add_u32 m0, m0, 0x400
	v_mfma_f32_16x16x32_bf16 v[20:23], v[124:127], v[120:123], v[20:23]
	global_load_lds_dwordx4 v155, s[56:57]
	v_mfma_f32_16x16x32_bf16 v[12:15], v[128:131], v[80:83], v[12:15]
	s_waitcnt lgkmcnt(0)
	v_mfma_f32_16x16x32_bf16 v[48:51], v[132:135], v[80:83], v[48:51]
	v_mfma_f32_16x16x32_bf16 v[16:19], v[128:131], v[92:95], v[16:19]
	v_mfma_f32_16x16x32_bf16 v[44:47], v[132:135], v[92:95], v[44:47]
	v_mfma_f32_16x16x32_bf16 v[56:59], v[128:131], v[116:119], v[56:59]
	v_mfma_f32_16x16x32_bf16 v[52:55], v[128:131], v[120:123], v[52:55]
	v_mfma_f32_16x16x32_bf16 v[40:43], v[132:135], v[116:119], v[40:43]
	v_mfma_f32_16x16x32_bf16 v[60:63], v[132:135], v[120:123], v[60:63]
	s_waitcnt vmcnt(0)
	s_barrier
	s_add_u32 s54, s54, 0x80
	s_addc_u32 s55, s55, 0
	s_add_u32 s56, s56, 0x80
	s_addc_u32 s57, s57, 0
	ds_read_b128 v[64:67], v156 offset:32768
	ds_read_b128 v[68:71], v158 offset:49152
	ds_read_b128 v[80:83], v159 offset:49152
	ds_read_b128 v[72:75], v157 offset:32768
	ds_read_b128 v[76:79], v158 offset:51200
	ds_read_b128 v[92:95], v159 offset:51200
	ds_read_b128 v[84:87], v158 offset:53248
	ds_read_b128 v[116:119], v159 offset:53248
	ds_read_b128 v[88:91], v158 offset:55296
	ds_read_b128 v[120:123], v159 offset:55296
	s_waitcnt lgkmcnt(8)
	v_mfma_f32_16x16x32_bf16 v[36:39], v[64:67], v[68:71], v[36:39]
	s_waitcnt lgkmcnt(5)
	v_mfma_f32_16x16x32_bf16 v[32:35], v[64:67], v[76:79], v[32:35]
	s_waitcnt lgkmcnt(3)
	s_add_u32 m0, s58, 0x0
	v_mfma_f32_16x16x32_bf16 v[28:31], v[64:67], v[84:87], v[28:31]
	global_load_lds_dwordx4 v152, s[54:55]
	s_waitcnt lgkmcnt(1)
	v_mfma_f32_16x16x32_bf16 v[24:27], v[64:67], v[88:91], v[24:27]
	ds_read_b128 v[64:67], v156 offset:34816
	ds_read_b128 v[124:127], v157 offset:34816
	s_waitcnt lgkmcnt(1)
	v_mfma_f32_16x16x32_bf16 v[8:11], v[64:67], v[68:71], v[8:11]
	s_add_u32 m0, m0, 0x400
	v_mfma_f32_16x16x32_bf16 v[4:7], v[64:67], v[76:79], v[4:7]
	global_load_lds_dwordx4 v153, s[54:55]
	v_mfma_f32_16x16x32_bf16 v[0:3], v[64:67], v[84:87], v[0:3]
	v_mfma_f32_16x16x32_bf16 v[20:23], v[64:67], v[88:91], v[20:23]
	ds_read_b128 v[64:67], v156 offset:36864
	ds_read_b128 v[128:131], v157 offset:36864
	s_waitcnt lgkmcnt(1)
	s_add_u32 m0, m0, 0x400
	v_mfma_f32_16x16x32_bf16 v[12:15], v[64:67], v[68:71], v[12:15]
	global_load_lds_dwordx4 v154, s[54:55]
	v_mfma_f32_16x16x32_bf16 v[16:19], v[64:67], v[76:79], v[16:19]
	v_mfma_f32_16x16x32_bf16 v[56:59], v[64:67], v[84:87], v[56:59]
	s_add_u32 m0, m0, 0x400
	v_mfma_f32_16x16x32_bf16 v[52:55], v[64:67], v[88:91], v[52:55]
	global_load_lds_dwordx4 v155, s[54:55]
	ds_read_b128 v[64:67], v156 offset:38912
	ds_read_b128 v[132:135], v157 offset:38912
	s_waitcnt lgkmcnt(1)
	v_mfma_f32_16x16x32_bf16 v[48:51], v[64:67], v[68:71], v[48:51]
	v_mfma_f32_16x16x32_bf16 v[44:47], v[64:67], v[76:79], v[44:47]
	s_add_u32 m0, m0, 0x3400
	v_mfma_f32_16x16x32_bf16 v[40:43], v[64:67], v[84:87], v[40:43]
	global_load_lds_dwordx4 v152, s[56:57]
	v_mfma_f32_16x16x32_bf16 v[60:63], v[64:67], v[88:91], v[60:63]
	v_mfma_f32_16x16x32_bf16 v[36:39], v[72:75], v[80:83], v[36:39]
	s_add_u32 m0, m0, 0x400
	v_mfma_f32_16x16x32_bf16 v[32:35], v[72:75], v[92:95], v[32:35]
	global_load_lds_dwordx4 v153, s[56:57]
	v_mfma_f32_16x16x32_bf16 v[28:31], v[72:75], v[116:119], v[28:31]
	v_mfma_f32_16x16x32_bf16 v[24:27], v[72:75], v[120:123], v[24:27]
	s_add_u32 m0, m0, 0x400
	v_mfma_f32_16x16x32_bf16 v[8:11], v[124:127], v[80:83], v[8:11]
	global_load_lds_dwordx4 v154, s[56:57]
	v_mfma_f32_16x16x32_bf16 v[4:7], v[124:127], v[92:95], v[4:7]
	v_mfma_f32_16x16x32_bf16 v[0:3], v[124:127], v[116:119], v[0:3]
	s_add_u32 m0, m0, 0x400
	v_mfma_f32_16x16x32_bf16 v[20:23], v[124:127], v[120:123], v[20:23]
	global_load_lds_dwordx4 v155, s[56:57]
	v_mfma_f32_16x16x32_bf16 v[12:15], v[128:131], v[80:83], v[12:15]
	s_waitcnt lgkmcnt(0)
	v_mfma_f32_16x16x32_bf16 v[48:51], v[132:135], v[80:83], v[48:51]
	v_mfma_f32_16x16x32_bf16 v[16:19], v[128:131], v[92:95], v[16:19]
	v_mfma_f32_16x16x32_bf16 v[44:47], v[132:135], v[92:95], v[44:47]
	v_mfma_f32_16x16x32_bf16 v[56:59], v[128:131], v[116:119], v[56:59]
	v_mfma_f32_16x16x32_bf16 v[52:55], v[128:131], v[120:123], v[52:55]
	v_mfma_f32_16x16x32_bf16 v[40:43], v[132:135], v[116:119], v[40:43]
	v_mfma_f32_16x16x32_bf16 v[60:63], v[132:135], v[120:123], v[60:63]
	s_waitcnt vmcnt(0)
	s_barrier
	s_add_i32 s59, s59, -1
	s_cmp_lg_u32 s59, 0
	s_cbranch_scc1 .Lg2_loop
	s_add_u32 s54, s54, 0x80
	s_addc_u32 s55, s55, 0
	s_add_u32 s56, s56, 0x80
	s_addc_u32 s57, s57, 0
	ds_read_b128 v[64:67], v156
	ds_read_b128 v[68:71], v158 offset:16384
	ds_read_b128 v[80:83], v159 offset:16384
	ds_read_b128 v[72:75], v157
	ds_read_b128 v[76:79], v158 offset:18432
	ds_read_b128 v[92:95], v159 offset:18432
	ds_read_b128 v[84:87], v158 offset:20480
	ds_read_b128 v[116:119], v159 offset:20480
	ds_read_b128 v[88:91], v158 offset:22528
	ds_read_b128 v[120:123], v159 offset:22528
	s_waitcnt lgkmcnt(8)
	v_mfma_f32_16x16x32_bf16 v[36:39], v[64:67], v[68:71], v[36:39]
	s_waitcnt lgkmcnt(5)
	v_mfma_f32_16x16x32_bf16 v[32:35], v[64:67], v[76:79], v[32:35]
	s_waitcnt lgkmcnt(3)
	s_add_u32 m0, s58, 0x8000
	v_mfma_f32_16x16x32_bf16 v[28:31], v[64:67], v[84:87], v[28:31]
	global_load_lds_dwordx4 v152, s[54:55]
	s_waitcnt lgkmcnt(1)
	v_mfma_f32_16x16x32_bf16 v[24:27], v[64:67], v[88:91], v[24:27]
	ds_read_b128 v[64:67], v156 offset:2048
	ds_read_b128 v[124:127], v157 offset:2048
	s_waitcnt lgkmcnt(1)
	v_mfma_f32_16x16x32_bf16 v[8:11], v[64:67], v[68:71], v[8:11]
	s_add_u32 m0, m0, 0x400
	v_mfma_f32_16x16x32_bf16 v[4:7], v[64:67], v[76:79], v[4:7]
	global_load_lds_dwordx4 v153, s[54:55]
	v_mfma_f32_16x16x32_bf16 v[0:3], v[64:67], v[84:87], v[0:3]
	v_mfma_f32_16x16x32_bf16 v[20:23], v[64:67], v[88:91], v[20:23]
	ds_read_b128 v[64:67], v156 offset:4096
	ds_read_b128 v[128:131], v157 offset:4096
	s_waitcnt lgkmcnt(1)
	s_add_u32 m0, m0, 0x400
	v_mfma_f32_16x16x32_bf16 v[12:15], v[64:67], v[68:71], v[12:15]
	global_load_lds_dwordx4 v154, s[54:55]
	v_mfma_f32_16x16x32_bf16 v[16:19], v[64:67], v[76:79], v[16:19]
	v_mfma_f32_16x16x32_bf16 v[56:59], v[64:67], v[84:87], v[56:59]
	s_add_u32 m0, m0, 0x400
	v_mfma_f32_16x16x32_bf16 v[52:55], v[64:67], v[88:91], v[52:55]
	global_load_lds_dwordx4 v155, s[54:55]
	ds_read_b128 v[64:67], v156 offset:6144
	ds_read_b128 v[132:135], v157 offset:6144
	s_waitcnt lgkmcnt(1)
	v_mfma_f32_16x16x32_bf16 v[48:51], v[64:67], v[68:71], v[48:51]
	v_mfma_f32_16x16x32_bf16 v[44:47], v[64:67], v[76:79], v[44:47]
	s_add_u32 m0, m0, 0x3400
	v_mfma_f32_16x16x32_bf16 v[40:43], v[64:67], v[84:87], v[40:43]
	global_load_lds_dwordx4 v152, s[56:57]
	v_mfma_f32_16x16x32_bf16 v[60:63], v[64:67], v[88:91], v[60:63]
	v_mfma_f32_16x16x32_bf16 v[36:39], v[72:75], v[80:83], v[36:39]
	s_add_u32 m0, m0, 0x400
	v_mfma_f32_16x16x32_bf16 v[32:35], v[72:75], v[92:95], v[32:35]
	global_load_lds_dwordx4 v153, s[56:57]
	v_mfma_f32_16x16x32_bf16 v[28:31], v[72:75], v[116:119], v[28:31]
	v_mfma_f32_16x16x32_bf16 v[24:27], v[72:75], v[120:123], v[24:27]
	s_add_u32 m0, m0, 0x400
	v_mfma_f32_16x16x32_bf16 v[8:11], v[124:127], v[80:83], v[8:11]
	global_load_lds_dwordx4 v154, s[56:57]
	v_mfma_f32_16x16x32_bf16 v[4:7], v[124:127], v[92:95], v[4:7]
	v_mfma_f32_16x16x32_bf16 v[0:3], v[124:127], v[116:119], v[0:3]
	s_add_u32 m0, m0, 0x400
	v_mfma_f32_16x16x32_bf16 v[20:23], v[124:127], v[120:123], v[20:23]
	global_load_lds_dwordx4 v155, s[56:57]
	v_mfma_f32_16x16x32_bf16 v[12:15], v[128:131], v[80:83], v[12:15]
	s_waitcnt lgkmcnt(0)
	v_mfma_f32_16x16x32_bf16 v[48:51], v[132:135], v[80:83], v[48:51]
	v_mfma_f32_16x16x32_bf16 v[16:19], v[128:131], v[92:95], v[16:19]
	v_mfma_f32_16x16x32_bf16 v[44:47], v[132:135], v[92:95], v[44:47]
	v_mfma_f32_16x16x32_bf16 v[56:59], v[128:131], v[116:119], v[56:59]
	v_mfma_f32_16x16x32_bf16 v[52:55], v[128:131], v[120:123], v[52:55]
	v_mfma_f32_16x16x32_bf16 v[40:43], v[132:135], v[116:119], v[40:43]
	v_mfma_f32_16x16x32_bf16 v[60:63], v[132:135], v[120:123], v[60:63]
	s_waitcnt vmcnt(0)
	s_barrier
	s_add_i32 s63, s6, s92
	s_cmp_lt_i32 s63, s21
	s_cbranch_scc0 .Lg2_last_nodma
	s_add_i32 s63, s63, s22
	s_mul_hi_i32 s64, s63, 0x8d3dcb09
	s_add_i32 s64, s64, s63
	s_lshr_b32 s65, s64, 31
	s_ashr_i32 s64, s64, 4
	s_add_i32 s64, s64, s65
	s_mul_i32 s65, s64, 29
	s_lshl_b32 s64, s64, 7
	s_sub_i32 s63, s63, s65
	s_lshl_b32 s63, s63, 7
	s_lshl_b32 s62, s64, 11
	s_add_u32 s54, s82, s62
	s_addc_u32 s55, s83, 0
	s_add_u32 s54, s54, 0x3000000
	s_addc_u32 s55, s55, 0
	s_lshl_b32 s62, s63, 11
	s_add_u32 s56, s60, s62
	s_addc_u32 s57, s61, 0
	ds_read_b128 v[64:67], v156 offset:32768
	ds_read_b128 v[68:71], v158 offset:49152
	ds_read_b128 v[80:83], v159 offset:49152
	ds_read_b128 v[72:75], v157 offset:32768
	ds_read_b128 v[76:79], v158 offset:51200
	ds_read_b128 v[92:95], v159 offset:51200
	ds_read_b128 v[84:87], v158 offset:53248
	ds_read_b128 v[116:119], v159 offset:53248
	ds_read_b128 v[88:91], v158 offset:55296
	ds_read_b128 v[120:123], v159 offset:55296
	s_waitcnt lgkmcnt(8)
	v_mfma_f32_16x16x32_bf16 v[36:39], v[64:67], v[68:71], v[36:39]
	s_waitcnt lgkmcnt(5)
	v_mfma_f32_16x16x32_bf16 v[32:35], v[64:67], v[76:79], v[32:35]
	s_waitcnt lgkmcnt(3)
	s_add_u32 m0, s58, 0x0
	v_mfma_f32_16x16x32_bf16 v[28:31], v[64:67], v[84:87], v[28:31]
	global_load_lds_dwordx4 v152, s[54:55]
	s_waitcnt lgkmcnt(1)
	v_mfma_f32_16x16x32_bf16 v[24:27], v[64:67], v[88:91], v[24:27]
	ds_read_b128 v[64:67], v156 offset:34816
	ds_read_b128 v[124:127], v157 offset:34816
	s_waitcnt lgkmcnt(1)
	v_mfma_f32_16x16x32_bf16 v[8:11], v[64:67], v[68:71], v[8:11]
	s_add_u32 m0, m0, 0x400
	v_mfma_f32_16x16x32_bf16 v[4:7], v[64:67], v[76:79], v[4:7]
	global_load_lds_dwordx4 v153, s[54:55]
	v_mfma_f32_16x16x32_bf16 v[0:3], v[64:67], v[84:87], v[0:3]
	v_mfma_f32_16x16x32_bf16 v[20:23], v[64:67], v[88:91], v[20:23]
	ds_read_b128 v[64:67], v156 offset:36864
	ds_read_b128 v[128:131], v157 offset:36864
	s_waitcnt lgkmcnt(1)
	s_add_u32 m0, m0, 0x400
	v_mfma_f32_16x16x32_bf16 v[12:15], v[64:67], v[68:71], v[12:15]
	global_load_lds_dwordx4 v154, s[54:55]
	v_mfma_f32_16x16x32_bf16 v[16:19], v[64:67], v[76:79], v[16:19]
	v_mfma_f32_16x16x32_bf16 v[56:59], v[64:67], v[84:87], v[56:59]
	s_add_u32 m0, m0, 0x400
	v_mfma_f32_16x16x32_bf16 v[52:55], v[64:67], v[88:91], v[52:55]
	global_load_lds_dwordx4 v155, s[54:55]
	ds_read_b128 v[64:67], v156 offset:38912
	ds_read_b128 v[132:135], v157 offset:38912
	s_waitcnt lgkmcnt(1)
	v_mfma_f32_16x16x32_bf16 v[48:51], v[64:67], v[68:71], v[48:51]
	v_mfma_f32_16x16x32_bf16 v[44:47], v[64:67], v[76:79], v[44:47]
	s_add_u32 m0, m0, 0x3400
	v_mfma_f32_16x16x32_bf16 v[40:43], v[64:67], v[84:87], v[40:43]
	global_load_lds_dwordx4 v152, s[56:57]
	v_mfma_f32_16x16x32_bf16 v[60:63], v[64:67], v[88:91], v[60:63]
	v_mfma_f32_16x16x32_bf16 v[36:39], v[72:75], v[80:83], v[36:39]
	s_add_u32 m0, m0, 0x400
	v_mfma_f32_16x16x32_bf16 v[32:35], v[72:75], v[92:95], v[32:35]
	global_load_lds_dwordx4 v153, s[56:57]
	v_mfma_f32_16x16x32_bf16 v[28:31], v[72:75], v[116:119], v[28:31]
	v_mfma_f32_16x16x32_bf16 v[24:27], v[72:75], v[120:123], v[24:27]
	s_add_u32 m0, m0, 0x400
	v_mfma_f32_16x16x32_bf16 v[8:11], v[124:127], v[80:83], v[8:11]
	global_load_lds_dwordx4 v154, s[56:57]
	v_mfma_f32_16x16x32_bf16 v[4:7], v[124:127], v[92:95], v[4:7]
	v_mfma_f32_16x16x32_bf16 v[0:3], v[124:127], v[116:119], v[0:3]
	s_add_u32 m0, m0, 0x400
	v_mfma_f32_16x16x32_bf16 v[20:23], v[124:127], v[120:123], v[20:23]
	global_load_lds_dwordx4 v155, s[56:57]
	v_mfma_f32_16x16x32_bf16 v[12:15], v[128:131], v[80:83], v[12:15]
	s_waitcnt lgkmcnt(0)
	v_mfma_f32_16x16x32_bf16 v[48:51], v[132:135], v[80:83], v[48:51]
	v_mfma_f32_16x16x32_bf16 v[16:19], v[128:131], v[92:95], v[16:19]
	v_mfma_f32_16x16x32_bf16 v[44:47], v[132:135], v[92:95], v[44:47]
	v_mfma_f32_16x16x32_bf16 v[56:59], v[128:131], v[116:119], v[56:59]
	v_mfma_f32_16x16x32_bf16 v[52:55], v[128:131], v[120:123], v[52:55]
	v_mfma_f32_16x16x32_bf16 v[40:43], v[132:135], v[116:119], v[40:43]
	v_mfma_f32_16x16x32_bf16 v[60:63], v[132:135], v[120:123], v[60:63]
	s_branch .Lg2_epi
.Lg2_last_nodma:
	ds_read_b128 v[64:67], v156 offset:32768
	ds_read_b128 v[68:71], v158 offset:49152
	ds_read_b128 v[80:83], v159 offset:49152
	ds_read_b128 v[72:75], v157 offset:32768
	ds_read_b128 v[76:79], v158 offset:51200
	ds_read_b128 v[92:95], v159 offset:51200
	ds_read_b128 v[84:87], v158 offset:53248
	ds_read_b128 v[116:119], v159 offset:53248
	ds_read_b128 v[88:91], v158 offset:55296
	ds_read_b128 v[120:123], v159 offset:55296
	s_waitcnt lgkmcnt(8)
	v_mfma_f32_16x16x32_bf16 v[36:39], v[64:67], v[68:71], v[36:39]
	s_waitcnt lgkmcnt(5)
	v_mfma_f32_16x16x32_bf16 v[32:35], v[64:67], v[76:79], v[32:35]
	s_waitcnt lgkmcnt(3)
	v_mfma_f32_16x16x32_bf16 v[28:31], v[64:67], v[84:87], v[28:31]
	s_waitcnt lgkmcnt(1)
	v_mfma_f32_16x16x32_bf16 v[24:27], v[64:67], v[88:91], v[24:27]
	ds_read_b128 v[64:67], v156 offset:34816
	ds_read_b128 v[124:127], v157 offset:34816
	s_waitcnt lgkmcnt(1)
	v_mfma_f32_16x16x32_bf16 v[8:11], v[64:67], v[68:71], v[8:11]
	v_mfma_f32_16x16x32_bf16 v[4:7], v[64:67], v[76:79], v[4:7]
	v_mfma_f32_16x16x32_bf16 v[0:3], v[64:67], v[84:87], v[0:3]
	v_mfma_f32_16x16x32_bf16 v[20:23], v[64:67], v[88:91], v[20:23]
	ds_read_b128 v[64:67], v156 offset:36864
	ds_read_b128 v[128:131], v157 offset:36864
	s_waitcnt lgkmcnt(1)
	v_mfma_f32_16x16x32_bf16 v[12:15], v[64:67], v[68:71], v[12:15]
	v_mfma_f32_16x16x32_bf16 v[16:19], v[64:67], v[76:79], v[16:19]
	v_mfma_f32_16x16x32_bf16 v[56:59], v[64:67], v[84:87], v[56:59]
	v_mfma_f32_16x16x32_bf16 v[52:55], v[64:67], v[88:91], v[52:55]
	ds_read_b128 v[64:67], v156 offset:38912
	ds_read_b128 v[132:135], v157 offset:38912
	s_waitcnt lgkmcnt(1)
	v_mfma_f32_16x16x32_bf16 v[48:51], v[64:67], v[68:71], v[48:51]
	v_mfma_f32_16x16x32_bf16 v[44:47], v[64:67], v[76:79], v[44:47]
	v_mfma_f32_16x16x32_bf16 v[40:43], v[64:67], v[84:87], v[40:43]
	v_mfma_f32_16x16x32_bf16 v[60:63], v[64:67], v[88:91], v[60:63]
	v_mfma_f32_16x16x32_bf16 v[36:39], v[72:75], v[80:83], v[36:39]
	v_mfma_f32_16x16x32_bf16 v[32:35], v[72:75], v[92:95], v[32:35]
	v_mfma_f32_16x16x32_bf16 v[28:31], v[72:75], v[116:119], v[28:31]
	v_mfma_f32_16x16x32_bf16 v[24:27], v[72:75], v[120:123], v[24:27]
	v_mfma_f32_16x16x32_bf16 v[8:11], v[124:127], v[80:83], v[8:11]
	v_mfma_f32_16x16x32_bf16 v[4:7], v[124:127], v[92:95], v[4:7]
	v_mfma_f32_16x16x32_bf16 v[0:3], v[124:127], v[116:119], v[0:3]
	v_mfma_f32_16x16x32_bf16 v[20:23], v[124:127], v[120:123], v[20:23]
	v_mfma_f32_16x16x32_bf16 v[12:15], v[128:131], v[80:83], v[12:15]
	s_waitcnt lgkmcnt(0)
	v_mfma_f32_16x16x32_bf16 v[48:51], v[132:135], v[80:83], v[48:51]
	v_mfma_f32_16x16x32_bf16 v[16:19], v[128:131], v[92:95], v[16:19]
	v_mfma_f32_16x16x32_bf16 v[44:47], v[132:135], v[92:95], v[44:47]
	v_mfma_f32_16x16x32_bf16 v[56:59], v[128:131], v[116:119], v[56:59]
	v_mfma_f32_16x16x32_bf16 v[52:55], v[128:131], v[120:123], v[52:55]
	v_mfma_f32_16x16x32_bf16 v[40:43], v[132:135], v[116:119], v[40:43]
	v_mfma_f32_16x16x32_bf16 v[60:63], v[132:135], v[120:123], v[60:63]
.Lg2_epi:
	s_nop 7
	s_nop 7
	s_movk_i32 s4, 0x3a00
	s_add_i32 s6, s6, s92
	v_add_u32_e32 v68, s3, v111
	s_ashr_i32 s3, s2, 31
	v_lshl_add_u64 v[64:65], s[2:3], 2, v[100:101]
	v_mad_i64_i32 v[66:67], s[2:3], v68, s4, v[64:65]
	global_store_dword v[66:67], v36, off
	global_store_dword v[66:67], v32, off offset:64
	global_store_dword v[66:67], v28, off offset:128
	global_store_dword v[66:67], v24, off offset:192
	v_or_b32_e32 v24, 1, v68
	v_mad_i64_i32 v[66:67], s[2:3], v24, s4, v[64:65]
	v_or_b32_e32 v24, 2, v68
	global_store_dword v[66:67], v37, off
	global_store_dword v[66:67], v33, off offset:64
	global_store_dword v[66:67], v29, off offset:128
	global_store_dword v[66:67], v25, off offset:192
	v_mad_i64_i32 v[24:25], s[2:3], v24, s4, v[64:65]
	global_store_dword v[24:25], v38, off
	global_store_dword v[24:25], v34, off offset:64
	global_store_dword v[24:25], v30, off offset:128
	global_store_dword v[24:25], v26, off offset:192
	v_or_b32_e32 v24, 3, v68
	v_mad_i64_i32 v[24:25], s[2:3], v24, s4, v[64:65]
	global_store_dword v[24:25], v39, off
	global_store_dword v[24:25], v35, off offset:64
	global_store_dword v[24:25], v31, off offset:128
	global_store_dword v[24:25], v27, off offset:192
	v_or_b32_e32 v24, 16, v68
	v_mad_i64_i32 v[24:25], s[2:3], v24, s4, v[64:65]
	global_store_dword v[24:25], v8, off
	global_store_dword v[24:25], v4, off offset:64
	global_store_dword v[24:25], v0, off offset:128
	global_store_dword v[24:25], v20, off offset:192
	v_or_b32_e32 v0, 17, v68
	v_mad_i64_i32 v[24:25], s[2:3], v0, s4, v[64:65]
	v_or_b32_e32 v0, 18, v68
	global_store_dword v[24:25], v9, off
	global_store_dword v[24:25], v5, off offset:64
	global_store_dword v[24:25], v1, off offset:128
	global_store_dword v[24:25], v21, off offset:192
	v_mad_i64_i32 v[0:1], s[2:3], v0, s4, v[64:65]
	global_store_dword v[0:1], v10, off
	global_store_dword v[0:1], v6, off offset:64
	global_store_dword v[0:1], v2, off offset:128
	global_store_dword v[0:1], v22, off offset:192
	v_or_b32_e32 v0, 19, v68
	v_mad_i64_i32 v[0:1], s[2:3], v0, s4, v[64:65]
	global_store_dword v[0:1], v11, off
	global_store_dword v[0:1], v7, off offset:64
	global_store_dword v[0:1], v3, off offset:128
	global_store_dword v[0:1], v23, off offset:192
	v_or_b32_e32 v0, 32, v68
	v_mad_i64_i32 v[0:1], s[2:3], v0, s4, v[64:65]
	global_store_dword v[0:1], v12, off
	global_store_dword v[0:1], v16, off offset:64
	global_store_dword v[0:1], v56, off offset:128
	global_store_dword v[0:1], v52, off offset:192
	v_or_b32_e32 v0, 33, v68
	v_mad_i64_i32 v[0:1], s[2:3], v0, s4, v[64:65]
	global_store_dword v[0:1], v13, off
	global_store_dword v[0:1], v17, off offset:64
	global_store_dword v[0:1], v57, off offset:128
	global_store_dword v[0:1], v53, off offset:192
	v_or_b32_e32 v0, 34, v68
	v_mad_i64_i32 v[0:1], s[2:3], v0, s4, v[64:65]
	global_store_dword v[0:1], v14, off
	global_store_dword v[0:1], v18, off offset:64
	global_store_dword v[0:1], v58, off offset:128
	global_store_dword v[0:1], v54, off offset:192
	v_or_b32_e32 v0, 35, v68
	v_mad_i64_i32 v[0:1], s[2:3], v0, s4, v[64:65]
	global_store_dword v[0:1], v15, off
	global_store_dword v[0:1], v19, off offset:64
	global_store_dword v[0:1], v59, off offset:128
	global_store_dword v[0:1], v55, off offset:192
	v_or_b32_e32 v0, 48, v68
	v_mad_i64_i32 v[0:1], s[2:3], v0, s4, v[64:65]
	global_store_dword v[0:1], v48, off
	global_store_dword v[0:1], v44, off offset:64
	global_store_dword v[0:1], v40, off offset:128
	s_nop 4
	global_store_dword v[0:1], v60, off offset:192
	v_or_b32_e32 v0, 49, v68
	v_mad_i64_i32 v[0:1], s[2:3], v0, s4, v[64:65]
	global_store_dword v[0:1], v49, off
	global_store_dword v[0:1], v45, off offset:64
	global_store_dword v[0:1], v41, off offset:128
	global_store_dword v[0:1], v61, off offset:192
	v_or_b32_e32 v0, 50, v68
	v_mad_i64_i32 v[0:1], s[2:3], v0, s4, v[64:65]
	global_store_dword v[0:1], v50, off
	global_store_dword v[0:1], v46, off offset:64
	global_store_dword v[0:1], v42, off offset:128
	global_store_dword v[0:1], v62, off offset:192
	v_or_b32_e32 v0, 51, v68
	v_mad_i64_i32 v[0:1], s[2:3], v0, s4, v[64:65]
	s_cmp_ge_i32 s6, s21
	global_store_dword v[0:1], v51, off
	global_store_dword v[0:1], v47, off offset:64
	global_store_dword v[0:1], v43, off offset:128
	global_store_dword v[0:1], v63, off offset:192
	s_cbranch_scc0 .Lg2_next
